# P2 S5 state-increment GEMM: next K-slice tile loads issued right after the barrier that opens the current slice's MMA (into spare VGPRs) instead of after the MMA; on top of v126
# speedup vs baseline: 1.0104x; 1.0048x over previous
.LBB0_413:
	s_ashr_i32 s10, s9, 3
	s_and_b32 s11, s6, 0x380
	s_lshl_b32 s13, s10, 10
	s_lshl_b32 s12, s10, 7
	s_or_b32 s10, s13, s11
	s_ashr_i32 s13, s12, 31
	s_lshl_b64 s[12:13], s[12:13], 10
	v_mad_i64_i32 v[18:19], s[18:19], s10, v33, v[4:5]
	v_lshl_add_u64 v[14:15], v[18:19], 0, v[0:1]
	v_lshl_add_u64 v[26:27], v[6:7], 0, s[12:13]
	v_add_co_u32_e32 v28, vcc, s8, v14
	v_lshl_add_u64 v[20:21], v[26:27], 0, v[34:35]
	v_lshl_add_u64 v[16:17], v[18:19], 0, v[8:9]
	v_lshl_add_u64 v[18:19], v[18:19], 0, v[10:11]
	global_load_dwordx4 v[54:57], v[14:15], off
	global_load_dwordx4 v[58:61], v[16:17], off
	v_lshl_add_u64 v[22:23], v[26:27], 0, v[36:37]
	v_lshl_add_u64 v[24:25], v[26:27], 0, v[12:13]
	v_lshl_add_u64 v[26:27], v[26:27], 0, v[38:39]
	v_addc_co_u32_e32 v29, vcc, 0, v15, vcc
	global_load_dwordx4 v[62:65], v[20:21], off
	global_load_dwordx4 v[66:69], v[22:23], off
	global_load_dwordx4 v[70:73], v[24:25], off
	global_load_dwordx4 v[74:77], v[26:27], off
	global_load_dwordx4 v[78:81], v[28:29], off
	global_load_dwordx4 v[82:85], v[18:19], off
	v_lshl_add_u64 v[28:29], v[14:15], 0, s[4:5]
	s_add_i32 s9, s9, s92
	s_add_i32 s6, s6, s7
	s_cmpk_gt_i32 s9, 0xff
	s_waitcnt vmcnt(0)
	ds_write_b128 v44, v[54:57]
	ds_write_b128 v45, v[58:61]
	ds_write_b128 v44, v[78:81] offset:17408
	ds_write_b128 v46, v[82:85]
	ds_write_b128 v44, v[62:65] offset:34816
	ds_write_b128 v45, v[66:69] offset:34816
	ds_write_b128 v44, v[70:73] offset:52224
	ds_write_b128 v46, v[74:77] offset:34816
	s_waitcnt lgkmcnt(0)
	s_barrier
	global_load_dwordx4 v[132:135], v[16:17], off offset:256
	global_load_dwordx4 v[136:139], v[14:15], off offset:256
	global_load_dwordx4 v[140:143], v[18:19], off offset:256
	global_load_dwordx4 v[144:147], v[28:29], off offset:256
	global_load_dwordx4 v[148:151], v[22:23], off offset:256
	global_load_dwordx4 v[152:155], v[20:21], off offset:256
	global_load_dwordx4 v[156:159], v[24:25], off offset:256
	global_load_dwordx4 v[160:163], v[26:27], off offset:256
	ds_read_b128 v[54:57], v49 offset:34816
	ds_read_b128 v[58:61], v50
	ds_read_b128 v[62:65], v50 offset:64
	ds_read_b128 v[66:69], v49 offset:34880
	ds_read_b128 v[70:73], v49 offset:39168
	ds_read_b128 v[74:77], v49 offset:39232
	ds_read_b128 v[78:81], v49 offset:43520
	ds_read_b128 v[82:85], v49 offset:43584
	ds_read_b128 v[86:89], v51 offset:34816
	ds_read_b128 v[90:93], v51 offset:34880
	s_waitcnt lgkmcnt(8)
	v_mfma_f32_16x16x32_bf16 v[54:57], v[54:57], v[58:61], 0
	ds_read_b128 v[94:97], v49 offset:52224
	ds_read_b128 v[98:101], v49 offset:52288
	ds_read_b128 v[102:105], v49 offset:56576
	ds_read_b128 v[106:109], v49 offset:56640
	ds_read_b128 v[110:113], v49 offset:60928
	ds_read_b128 v[114:117], v49 offset:60992
	s_waitcnt lgkmcnt(11)
	v_mfma_f32_16x16x32_bf16 v[70:73], v[70:73], v[58:61], 0
	ds_read_b128 v[118:121], v52 offset:34816
	ds_read_b128 v[122:125], v52 offset:34880
	s_waitcnt lgkmcnt(9)
	v_mfma_f32_16x16x32_bf16 v[86:89], v[86:89], v[58:61], 0
	v_mfma_f32_16x16x32_bf16 v[54:57], v[66:69], v[62:65], v[54:57]
	v_mfma_f32_16x16x32_bf16 v[66:69], v[74:77], v[62:65], v[70:73]
	s_waitcnt lgkmcnt(8)
	v_mfma_f32_16x16x32_bf16 v[74:77], v[90:93], v[62:65], v[86:89]
	ds_read_b128 v[90:93], v49 offset:34944
	v_mfma_f32_16x16x32_bf16 v[78:81], v[78:81], v[58:61], 0
	s_waitcnt lgkmcnt(8)
	v_mfma_f32_16x16x32_bf16 v[94:97], v[94:97], v[58:61], 0
	s_waitcnt lgkmcnt(6)
	v_mfma_f32_16x16x32_bf16 v[102:105], v[102:105], v[58:61], 0
	s_waitcnt lgkmcnt(4)
	v_mfma_f32_16x16x32_bf16 v[110:113], v[110:113], v[58:61], 0
	s_waitcnt lgkmcnt(2)
	v_mfma_f32_16x16x32_bf16 v[58:61], v[118:121], v[58:61], 0
	v_mfma_f32_16x16x32_bf16 v[70:73], v[82:85], v[62:65], v[78:81]
	v_mfma_f32_16x16x32_bf16 v[78:81], v[98:101], v[62:65], v[94:97]
	v_mfma_f32_16x16x32_bf16 v[82:85], v[106:109], v[62:65], v[102:105]
	v_mfma_f32_16x16x32_bf16 v[86:89], v[114:117], v[62:65], v[110:113]
	s_waitcnt lgkmcnt(1)
	v_mfma_f32_16x16x32_bf16 v[58:61], v[122:125], v[62:65], v[58:61]
	ds_read_b128 v[62:65], v50 offset:128
	ds_read_b128 v[94:97], v50 offset:192
	ds_read_b128 v[98:101], v49 offset:35008
	s_waitcnt lgkmcnt(2)
	v_mfma_f32_16x16x32_bf16 v[54:57], v[90:93], v[62:65], v[54:57]
	ds_read_b128 v[90:93], v49 offset:39296
	ds_read_b128 v[102:105], v49 offset:39360
	s_waitcnt lgkmcnt(1)
	v_mfma_f32_16x16x32_bf16 v[66:69], v[90:93], v[62:65], v[66:69]
	ds_read_b128 v[90:93], v49 offset:43648
	ds_read_b128 v[106:109], v49 offset:43712
	s_waitcnt lgkmcnt(1)
	v_mfma_f32_16x16x32_bf16 v[70:73], v[90:93], v[62:65], v[70:73]
	ds_read_b128 v[90:93], v51 offset:34944
	ds_read_b128 v[110:113], v51 offset:35008
	s_waitcnt lgkmcnt(1)
	v_mfma_f32_16x16x32_bf16 v[74:77], v[90:93], v[62:65], v[74:77]
	ds_read_b128 v[90:93], v49 offset:52352
	ds_read_b128 v[114:117], v49 offset:52416
	s_waitcnt lgkmcnt(1)
	v_mfma_f32_16x16x32_bf16 v[78:81], v[90:93], v[62:65], v[78:81]
	ds_read_b128 v[90:93], v49 offset:56704
	ds_read_b128 v[118:121], v49 offset:56768
	s_waitcnt lgkmcnt(1)
	v_mfma_f32_16x16x32_bf16 v[82:85], v[90:93], v[62:65], v[82:85]
	ds_read_b128 v[90:93], v49 offset:61056
	ds_read_b128 v[122:125], v49 offset:61120
	s_waitcnt lgkmcnt(1)
	v_mfma_f32_16x16x32_bf16 v[86:89], v[90:93], v[62:65], v[86:89]
	ds_read_b128 v[90:93], v52 offset:34944
	ds_read_b128 v[126:129], v52 offset:35008
	s_waitcnt lgkmcnt(1)
	v_mfma_f32_16x16x32_bf16 v[58:61], v[90:93], v[62:65], v[58:61]
	v_mfma_f32_16x16x32_bf16 v[54:57], v[98:101], v[94:97], v[54:57]
	v_mfma_f32_16x16x32_bf16 v[62:65], v[102:105], v[94:97], v[66:69]
	v_mfma_f32_16x16x32_bf16 v[66:69], v[106:109], v[94:97], v[70:73]
	s_nop 2
	v_mfma_f32_16x16x32_bf16 v[74:77], v[110:113], v[94:97], v[74:77]
	v_mfma_f32_16x16x32_bf16 v[78:81], v[114:117], v[94:97], v[78:81]
	v_mfma_f32_16x16x32_bf16 v[82:85], v[118:121], v[94:97], v[82:85]
	s_waitcnt lgkmcnt(0)
	s_barrier
	v_mfma_f32_16x16x32_bf16 v[86:89], v[122:125], v[94:97], v[86:89]
	s_waitcnt vmcnt(6)
	ds_write_b128 v44, v[136:139]
	ds_write_b128 v45, v[132:135]
	s_waitcnt vmcnt(4)
	ds_write_b128 v44, v[144:147] offset:17408
	ds_write_b128 v46, v[140:143]
	s_waitcnt vmcnt(2)
	ds_write_b128 v44, v[152:155] offset:34816
	ds_write_b128 v45, v[148:151] offset:34816
	s_waitcnt vmcnt(1)
	ds_write_b128 v44, v[156:159] offset:52224
	s_waitcnt vmcnt(0)
	ds_write_b128 v46, v[160:163] offset:34816
	v_mfma_f32_16x16x32_bf16 v[58:61], v[126:129], v[94:97], v[58:61]
	s_waitcnt lgkmcnt(0)
	s_barrier
	global_load_dwordx4 v[132:135], v[16:17], off offset:512
	global_load_dwordx4 v[136:139], v[14:15], off offset:512
	global_load_dwordx4 v[140:143], v[18:19], off offset:512
	global_load_dwordx4 v[144:147], v[28:29], off offset:512
	global_load_dwordx4 v[148:151], v[22:23], off offset:512
	global_load_dwordx4 v[152:155], v[20:21], off offset:512
	global_load_dwordx4 v[156:159], v[24:25], off offset:512
	global_load_dwordx4 v[160:163], v[26:27], off offset:512
	ds_read_b128 v[70:73], v49 offset:34816
	ds_read_b128 v[90:93], v50
	ds_read_b128 v[94:97], v50 offset:64
	ds_read_b128 v[98:101], v49 offset:34880
	s_waitcnt lgkmcnt(2)
	v_mfma_f32_16x16x32_bf16 v[54:57], v[70:73], v[90:93], v[54:57]
	ds_read_b128 v[70:73], v49 offset:39168
	ds_read_b128 v[102:105], v49 offset:39232
	s_waitcnt lgkmcnt(1)
	v_mfma_f32_16x16x32_bf16 v[62:65], v[70:73], v[90:93], v[62:65]
	ds_read_b128 v[70:73], v49 offset:43520
	ds_read_b128 v[106:109], v49 offset:43584
	s_waitcnt lgkmcnt(1)
	v_mfma_f32_16x16x32_bf16 v[66:69], v[70:73], v[90:93], v[66:69]
	ds_read_b128 v[70:73], v51 offset:34816
	ds_read_b128 v[110:113], v51 offset:34880
	s_waitcnt lgkmcnt(1)
	v_mfma_f32_16x16x32_bf16 v[70:73], v[70:73], v[90:93], v[74:77]
	s_nop 2
	ds_read_b128 v[74:77], v49 offset:52224
	ds_read_b128 v[114:117], v49 offset:52288
	s_waitcnt lgkmcnt(1)
	v_mfma_f32_16x16x32_bf16 v[74:77], v[74:77], v[90:93], v[78:81]
	s_nop 2
	ds_read_b128 v[78:81], v49 offset:56576
	ds_read_b128 v[118:121], v49 offset:56640
	s_waitcnt lgkmcnt(1)
	v_mfma_f32_16x16x32_bf16 v[78:81], v[78:81], v[90:93], v[82:85]
	s_nop 2
	ds_read_b128 v[82:85], v49 offset:60928
	ds_read_b128 v[122:125], v49 offset:60992
	s_waitcnt lgkmcnt(1)
	v_mfma_f32_16x16x32_bf16 v[82:85], v[82:85], v[90:93], v[86:89]
	s_nop 2
	ds_read_b128 v[86:89], v52 offset:34816
	ds_read_b128 v[126:129], v52 offset:34880
	s_waitcnt lgkmcnt(1)
	v_mfma_f32_16x16x32_bf16 v[58:61], v[86:89], v[90:93], v[58:61]
	ds_read_b128 v[86:89], v49 offset:34944
	v_mfma_f32_16x16x32_bf16 v[54:57], v[98:101], v[94:97], v[54:57]
	v_mfma_f32_16x16x32_bf16 v[62:65], v[102:105], v[94:97], v[62:65]
	v_mfma_f32_16x16x32_bf16 v[66:69], v[106:109], v[94:97], v[66:69]
	v_mfma_f32_16x16x32_bf16 v[70:73], v[110:113], v[94:97], v[70:73]
	v_mfma_f32_16x16x32_bf16 v[74:77], v[114:117], v[94:97], v[74:77]
	v_mfma_f32_16x16x32_bf16 v[78:81], v[118:121], v[94:97], v[78:81]
	v_mfma_f32_16x16x32_bf16 v[82:85], v[122:125], v[94:97], v[82:85]
	s_waitcnt lgkmcnt(1)
	v_mfma_f32_16x16x32_bf16 v[58:61], v[126:129], v[94:97], v[58:61]
	ds_read_b128 v[90:93], v50 offset:128
	ds_read_b128 v[94:97], v50 offset:192
	ds_read_b128 v[98:101], v49 offset:35008
	s_waitcnt lgkmcnt(2)
	v_mfma_f32_16x16x32_bf16 v[54:57], v[86:89], v[90:93], v[54:57]
	ds_read_b128 v[86:89], v49 offset:39296
	ds_read_b128 v[102:105], v49 offset:39360
	s_waitcnt lgkmcnt(1)
	v_mfma_f32_16x16x32_bf16 v[62:65], v[86:89], v[90:93], v[62:65]
	ds_read_b128 v[86:89], v49 offset:43648
	ds_read_b128 v[106:109], v49 offset:43712
	s_waitcnt lgkmcnt(1)
	v_mfma_f32_16x16x32_bf16 v[66:69], v[86:89], v[90:93], v[66:69]
	ds_read_b128 v[86:89], v51 offset:34944
	ds_read_b128 v[110:113], v51 offset:35008
	s_waitcnt lgkmcnt(1)
	v_mfma_f32_16x16x32_bf16 v[70:73], v[86:89], v[90:93], v[70:73]
	ds_read_b128 v[86:89], v49 offset:52352
	ds_read_b128 v[114:117], v49 offset:52416
	s_waitcnt lgkmcnt(1)
	v_mfma_f32_16x16x32_bf16 v[74:77], v[86:89], v[90:93], v[74:77]
	ds_read_b128 v[86:89], v49 offset:56704
	ds_read_b128 v[118:121], v49 offset:56768
	s_waitcnt lgkmcnt(1)
	v_mfma_f32_16x16x32_bf16 v[78:81], v[86:89], v[90:93], v[78:81]
	ds_read_b128 v[86:89], v49 offset:61056
	ds_read_b128 v[122:125], v49 offset:61120
	s_waitcnt lgkmcnt(1)
	v_mfma_f32_16x16x32_bf16 v[82:85], v[86:89], v[90:93], v[82:85]
	ds_read_b128 v[86:89], v52 offset:34944
	ds_read_b128 v[126:129], v52 offset:35008
	s_waitcnt lgkmcnt(1)
	v_mfma_f32_16x16x32_bf16 v[58:61], v[86:89], v[90:93], v[58:61]
	v_mfma_f32_16x16x32_bf16 v[54:57], v[98:101], v[94:97], v[54:57]
	v_mfma_f32_16x16x32_bf16 v[62:65], v[102:105], v[94:97], v[62:65]
	v_mfma_f32_16x16x32_bf16 v[66:69], v[106:109], v[94:97], v[66:69]
	v_mfma_f32_16x16x32_bf16 v[70:73], v[110:113], v[94:97], v[70:73]
	v_mfma_f32_16x16x32_bf16 v[74:77], v[114:117], v[94:97], v[74:77]
	v_mfma_f32_16x16x32_bf16 v[78:81], v[118:121], v[94:97], v[78:81]
	s_waitcnt lgkmcnt(0)
	s_barrier
	v_mfma_f32_16x16x32_bf16 v[82:85], v[122:125], v[94:97], v[82:85]
	s_waitcnt vmcnt(6)
	ds_write_b128 v44, v[136:139]
	ds_write_b128 v45, v[132:135]
	s_waitcnt vmcnt(4)
	ds_write_b128 v44, v[144:147] offset:17408
	ds_write_b128 v46, v[140:143]
	s_waitcnt vmcnt(2)
	ds_write_b128 v44, v[152:155] offset:34816
	ds_write_b128 v45, v[148:151] offset:34816
	s_waitcnt vmcnt(1)
	ds_write_b128 v44, v[156:159] offset:52224
	s_waitcnt vmcnt(0)
	ds_write_b128 v46, v[160:163] offset:34816
	v_mfma_f32_16x16x32_bf16 v[58:61], v[126:129], v[94:97], v[58:61]
	s_waitcnt lgkmcnt(0)
	s_barrier
	global_load_dwordx4 v[132:135], v[16:17], off offset:768
	global_load_dwordx4 v[136:139], v[14:15], off offset:768
	global_load_dwordx4 v[140:143], v[18:19], off offset:768
	global_load_dwordx4 v[144:147], v[28:29], off offset:768
	global_load_dwordx4 v[148:151], v[22:23], off offset:768
	global_load_dwordx4 v[152:155], v[20:21], off offset:768
	global_load_dwordx4 v[156:159], v[24:25], off offset:768
	global_load_dwordx4 v[160:163], v[26:27], off offset:768
	ds_read_b128 v[86:89], v49 offset:34816
	ds_read_b128 v[90:93], v50
	ds_read_b128 v[94:97], v50 offset:64
	ds_read_b128 v[98:101], v49 offset:34880
	s_waitcnt lgkmcnt(2)
	v_mfma_f32_16x16x32_bf16 v[54:57], v[86:89], v[90:93], v[54:57]
	ds_read_b128 v[86:89], v49 offset:39168
	ds_read_b128 v[102:105], v49 offset:39232
	s_waitcnt lgkmcnt(1)
	v_mfma_f32_16x16x32_bf16 v[62:65], v[86:89], v[90:93], v[62:65]
	ds_read_b128 v[86:89], v49 offset:43520
	ds_read_b128 v[106:109], v49 offset:43584
	s_waitcnt lgkmcnt(1)
	v_mfma_f32_16x16x32_bf16 v[66:69], v[86:89], v[90:93], v[66:69]
	ds_read_b128 v[86:89], v51 offset:34816
	ds_read_b128 v[110:113], v51 offset:34880
	s_waitcnt lgkmcnt(1)
	v_mfma_f32_16x16x32_bf16 v[70:73], v[86:89], v[90:93], v[70:73]
	ds_read_b128 v[86:89], v49 offset:52224
	ds_read_b128 v[114:117], v49 offset:52288
	s_waitcnt lgkmcnt(1)
	v_mfma_f32_16x16x32_bf16 v[74:77], v[86:89], v[90:93], v[74:77]
	ds_read_b128 v[86:89], v49 offset:56576
	ds_read_b128 v[118:121], v49 offset:56640
	s_waitcnt lgkmcnt(1)
	v_mfma_f32_16x16x32_bf16 v[78:81], v[86:89], v[90:93], v[78:81]
	ds_read_b128 v[86:89], v49 offset:60928
	ds_read_b128 v[122:125], v49 offset:60992
	s_waitcnt lgkmcnt(1)
	v_mfma_f32_16x16x32_bf16 v[82:85], v[86:89], v[90:93], v[82:85]
	ds_read_b128 v[86:89], v52 offset:34816
	ds_read_b128 v[126:129], v52 offset:34880
	s_waitcnt lgkmcnt(1)
	v_mfma_f32_16x16x32_bf16 v[58:61], v[86:89], v[90:93], v[58:61]
	ds_read_b128 v[86:89], v49 offset:34944
	v_mfma_f32_16x16x32_bf16 v[54:57], v[98:101], v[94:97], v[54:57]
	v_mfma_f32_16x16x32_bf16 v[62:65], v[102:105], v[94:97], v[62:65]
	v_mfma_f32_16x16x32_bf16 v[66:69], v[106:109], v[94:97], v[66:69]
	v_mfma_f32_16x16x32_bf16 v[70:73], v[110:113], v[94:97], v[70:73]
	v_mfma_f32_16x16x32_bf16 v[74:77], v[114:117], v[94:97], v[74:77]
	v_mfma_f32_16x16x32_bf16 v[78:81], v[118:121], v[94:97], v[78:81]
	v_mfma_f32_16x16x32_bf16 v[82:85], v[122:125], v[94:97], v[82:85]
	s_waitcnt lgkmcnt(1)
	v_mfma_f32_16x16x32_bf16 v[58:61], v[126:129], v[94:97], v[58:61]
	ds_read_b128 v[90:93], v50 offset:128
	ds_read_b128 v[94:97], v50 offset:192
	ds_read_b128 v[98:101], v49 offset:35008
	s_waitcnt lgkmcnt(2)
	v_mfma_f32_16x16x32_bf16 v[54:57], v[86:89], v[90:93], v[54:57]
	ds_read_b128 v[86:89], v49 offset:39296
	ds_read_b128 v[102:105], v49 offset:39360
	s_waitcnt lgkmcnt(1)
	v_mfma_f32_16x16x32_bf16 v[62:65], v[86:89], v[90:93], v[62:65]
	ds_read_b128 v[86:89], v49 offset:43648
	ds_read_b128 v[106:109], v49 offset:43712
	s_waitcnt lgkmcnt(1)
	v_mfma_f32_16x16x32_bf16 v[66:69], v[86:89], v[90:93], v[66:69]
	ds_read_b128 v[86:89], v51 offset:34944
	ds_read_b128 v[110:113], v51 offset:35008
	s_waitcnt lgkmcnt(1)
	v_mfma_f32_16x16x32_bf16 v[70:73], v[86:89], v[90:93], v[70:73]
	ds_read_b128 v[86:89], v49 offset:52352
	ds_read_b128 v[114:117], v49 offset:52416
	s_waitcnt lgkmcnt(1)
	v_mfma_f32_16x16x32_bf16 v[74:77], v[86:89], v[90:93], v[74:77]
	ds_read_b128 v[86:89], v49 offset:56704
	ds_read_b128 v[118:121], v49 offset:56768
	s_waitcnt lgkmcnt(1)
	v_mfma_f32_16x16x32_bf16 v[78:81], v[86:89], v[90:93], v[78:81]
	ds_read_b128 v[86:89], v49 offset:61056
	ds_read_b128 v[122:125], v49 offset:61120
	s_waitcnt lgkmcnt(1)
	v_mfma_f32_16x16x32_bf16 v[82:85], v[86:89], v[90:93], v[82:85]
	ds_read_b128 v[86:89], v52 offset:34944
	ds_read_b128 v[126:129], v52 offset:35008
	s_waitcnt lgkmcnt(1)
	v_mfma_f32_16x16x32_bf16 v[58:61], v[86:89], v[90:93], v[58:61]
	v_mfma_f32_16x16x32_bf16 v[54:57], v[98:101], v[94:97], v[54:57]
	s_nop 0
	v_mfma_f32_16x16x32_bf16 v[62:65], v[102:105], v[94:97], v[62:65]
	s_nop 0
	s_nop 0
	s_nop 0
	s_waitcnt lgkmcnt(0)
	s_barrier
	s_waitcnt vmcnt(6)
	ds_write_b128 v44, v[136:139]
	ds_write_b128 v45, v[132:135]
	s_waitcnt vmcnt(4)
	ds_write_b128 v44, v[144:147] offset:17408
	ds_write_b128 v46, v[140:143]
	s_waitcnt vmcnt(2)
	ds_write_b128 v44, v[152:155] offset:34816
	ds_write_b128 v45, v[148:151] offset:34816
	s_waitcnt vmcnt(1)
	ds_write_b128 v44, v[156:159] offset:52224
	s_waitcnt vmcnt(0)
	ds_write_b128 v46, v[160:163] offset:34816
	s_waitcnt lgkmcnt(0)
	s_barrier
	ds_read_b128 v[14:17], v49 offset:34816
	ds_read_b128 v[18:21], v50
	ds_read_b128 v[22:25], v50 offset:64
	ds_read_b128 v[26:29], v49 offset:34880
	s_waitcnt lgkmcnt(2)
	v_mfma_f32_16x16x32_bf16 v[14:17], v[14:17], v[18:21], v[54:57]
	s_nop 2
	ds_read_b128 v[54:57], v49 offset:39168
	ds_read_b128 v[86:89], v49 offset:39232
	v_mfma_f32_16x16x32_bf16 v[66:69], v[106:109], v[94:97], v[66:69]
	s_waitcnt lgkmcnt(1)
	v_mfma_f32_16x16x32_bf16 v[54:57], v[54:57], v[18:21], v[62:65]
	s_nop 2
	ds_read_b128 v[62:65], v49 offset:43520
	ds_read_b128 v[90:93], v49 offset:43584
	v_mfma_f32_16x16x32_bf16 v[70:73], v[110:113], v[94:97], v[70:73]
	v_mfma_f32_16x16x32_bf16 v[74:77], v[114:117], v[94:97], v[74:77]
	v_mfma_f32_16x16x32_bf16 v[78:81], v[118:121], v[94:97], v[78:81]
	v_mfma_f32_16x16x32_bf16 v[82:85], v[122:125], v[94:97], v[82:85]
	v_mfma_f32_16x16x32_bf16 v[58:61], v[126:129], v[94:97], v[58:61]
	s_waitcnt lgkmcnt(1)
	v_mfma_f32_16x16x32_bf16 v[62:65], v[62:65], v[18:21], v[66:69]
	s_nop 2
	ds_read_b128 v[66:69], v51 offset:34816
	ds_read_b128 v[94:97], v51 offset:34880
	s_waitcnt lgkmcnt(1)
	v_mfma_f32_16x16x32_bf16 v[66:69], v[66:69], v[18:21], v[70:73]
	s_nop 2
	ds_read_b128 v[70:73], v49 offset:52224
	ds_read_b128 v[98:101], v49 offset:52288
	s_waitcnt lgkmcnt(1)
	v_mfma_f32_16x16x32_bf16 v[70:73], v[70:73], v[18:21], v[74:77]
	s_nop 2
	ds_read_b128 v[74:77], v49 offset:56576
	ds_read_b128 v[102:105], v49 offset:56640
	s_waitcnt lgkmcnt(1)
	v_mfma_f32_16x16x32_bf16 v[74:77], v[74:77], v[18:21], v[78:81]
	s_nop 2
	ds_read_b128 v[78:81], v49 offset:60928
	ds_read_b128 v[106:109], v49 offset:60992
	s_waitcnt lgkmcnt(1)
	v_mfma_f32_16x16x32_bf16 v[78:81], v[78:81], v[18:21], v[82:85]
	s_nop 2
	ds_read_b128 v[82:85], v52 offset:34816
	ds_read_b128 v[110:113], v52 offset:34880
	s_waitcnt lgkmcnt(1)
	v_mfma_f32_16x16x32_bf16 v[18:21], v[82:85], v[18:21], v[58:61]
	v_mfma_f32_16x16x32_bf16 v[58:61], v[94:97], v[22:25], v[66:69]
	v_mfma_f32_16x16x32_bf16 v[66:69], v[102:105], v[22:25], v[74:77]
	s_nop 2
	ds_read_b128 v[74:77], v49 offset:34944
	v_mfma_f32_16x16x32_bf16 v[14:17], v[26:29], v[22:25], v[14:17]
	v_mfma_f32_16x16x32_bf16 v[26:29], v[86:89], v[22:25], v[54:57]
	v_mfma_f32_16x16x32_bf16 v[54:57], v[90:93], v[22:25], v[62:65]
	v_mfma_f32_16x16x32_bf16 v[62:65], v[98:101], v[22:25], v[70:73]
	v_mfma_f32_16x16x32_bf16 v[70:73], v[106:109], v[22:25], v[78:81]
	s_waitcnt lgkmcnt(1)
	v_mfma_f32_16x16x32_bf16 v[18:21], v[110:113], v[22:25], v[18:21]
	ds_read_b128 v[22:25], v50 offset:128
	ds_read_b128 v[78:81], v50 offset:192
	ds_read_b128 v[82:85], v49 offset:35008
	s_waitcnt lgkmcnt(2)
	v_mfma_f32_16x16x32_bf16 v[14:17], v[74:77], v[22:25], v[14:17]
	ds_read_b128 v[74:77], v49 offset:39296
	ds_read_b128 v[86:89], v49 offset:39360
	s_waitcnt lgkmcnt(1)
	v_mfma_f32_16x16x32_bf16 v[26:29], v[74:77], v[22:25], v[26:29]
	ds_read_b128 v[74:77], v49 offset:43648
	ds_read_b128 v[90:93], v49 offset:43712
	s_waitcnt lgkmcnt(1)
	v_mfma_f32_16x16x32_bf16 v[54:57], v[74:77], v[22:25], v[54:57]
	ds_read_b128 v[74:77], v51 offset:34944
	ds_read_b128 v[94:97], v51 offset:35008
	s_waitcnt lgkmcnt(1)
	v_mfma_f32_16x16x32_bf16 v[58:61], v[74:77], v[22:25], v[58:61]
	ds_read_b128 v[74:77], v49 offset:52352
	ds_read_b128 v[98:101], v49 offset:52416
	s_waitcnt lgkmcnt(1)
	v_mfma_f32_16x16x32_bf16 v[62:65], v[74:77], v[22:25], v[62:65]
	ds_read_b128 v[74:77], v49 offset:56704
	ds_read_b128 v[102:105], v49 offset:56768
	s_waitcnt lgkmcnt(1)
	v_mfma_f32_16x16x32_bf16 v[66:69], v[74:77], v[22:25], v[66:69]
	ds_read_b128 v[74:77], v49 offset:61056
	ds_read_b128 v[106:109], v49 offset:61120
	s_waitcnt lgkmcnt(1)
	v_mfma_f32_16x16x32_bf16 v[70:73], v[74:77], v[22:25], v[70:73]
	ds_read_b128 v[74:77], v52 offset:34944
	ds_read_b128 v[110:113], v52 offset:35008
	s_waitcnt lgkmcnt(0)
	s_barrier
	v_mfma_f32_16x16x32_bf16 v[18:21], v[74:77], v[22:25], v[18:21]
	v_add_u32_e32 v74, s10, v31
	v_ashrrev_i32_e32 v75, 31, v74
	v_mfma_f32_16x16x32_bf16 v[14:17], v[82:85], v[78:81], v[14:17]
	v_mfma_f32_16x16x32_bf16 v[22:25], v[86:89], v[78:81], v[26:29]
	v_mfma_f32_16x16x32_bf16 v[26:29], v[90:93], v[78:81], v[54:57]
	v_mfma_f32_16x16x32_bf16 v[54:57], v[94:97], v[78:81], v[58:61]
	v_mfma_f32_16x16x32_bf16 v[58:61], v[98:101], v[78:81], v[62:65]
	v_mfma_f32_16x16x32_bf16 v[62:65], v[102:105], v[78:81], v[66:69]
	s_nop 2
	v_lshlrev_b64 v[66:67], 9, v[74:75]
	v_lshl_add_u64 v[74:75], v[2:3], 0, v[66:67]
	v_mfma_f32_16x16x32_bf16 v[66:69], v[106:109], v[78:81], v[70:73]
	v_mfma_f32_16x16x32_bf16 v[18:21], v[110:113], v[78:81], v[18:21]
	global_store_dwordx4 v[74:75], v[14:17], off
	global_store_dwordx4 v[74:75], v[22:25], off offset:64
	global_store_dwordx4 v[74:75], v[26:29], off offset:128
	global_store_dwordx4 v[74:75], v[54:57], off offset:192
	global_store_dwordx4 v[74:75], v[58:61], off offset:256
	global_store_dwordx4 v[74:75], v[62:65], off offset:320
	s_nop 0
	global_store_dwordx4 v[74:75], v[66:69], off offset:384
	global_store_dwordx4 v[74:75], v[18:21], off offset:448
	s_cbranch_scc0 .LBB0_413
